# hot loop heads (top-k bit loop, score loop, attention tile loop) aligned to 64 bytes
# baseline (speedup 1.0000x reference)
; #define GAS __attribute__((address_space(1)))
; __device__ __forceinline__ void indexer_unit(const Args& a, LAS unsigned char* lds, LAS unsigned long long* maskl, int b, int qblk, int wave, int lane) {
;     ...
;     const int fr = lane & 15, fq = lane >> 4, t0 = qblk * 16; const size_t rowb = (size_t)b * SEQ;
;     bf16x8 af[8][2]; float wv[8][4];
; #pragma unroll
;     for (int rt = 0; rt < 8; ++rt) {
;         const GAS bf16* p = z + (rowb + t0 + 2 * rt + (fr >> 3)) * ZW + ZIQ + (fr & 7) * 64 + 8 * fq;
;         af[rt][0] = __builtin_nontemporal_load((const GAS bf16x8*)p); af[rt][1] = __builtin_nontemporal_load((const GAS bf16x8*)(p + 32));
;         const u32x2 w = *(const GAS u32x2*)(z + (rowb + t0 + 2 * rt + (fq >> 1)) * ZW + ZIW + 4 * (fq & 1));
;         wv[rt][0] = bflo(w.x); wv[rt][1] = bfhi(w.x); wv[rt][2] = bflo(w.y); wv[rt][3] = bfhi(w.y);
;     }
;     const int nkt = qblk + 1;
;     bf16x8 nb0, nb1;
;     { const int k0 = wave < nkt ? wave : 0; const GAS bf16* p = ikn + (rowb + 16 * k0 + fr) * 64 + 8 * fq; nb0 = *(const GAS bf16x8*)p; nb1 = *(const GAS bf16x8*)(p + 32); }
.LBB0_1082:
	v_readlane_b32 s2, v254, 44
	v_mov_b32_e32 v76, v252
	s_or_b32 s9, s8, s2
	s_lshl_b32 s76, s9, 4
	v_and_b32_e32 v5, 63, v76
	v_readlane_b32 s2, v254, 4
	s_cmp_gt_u32 s2, s9
	v_lshlrev_b32_e32 v84, 6, v5
	s_cbranch_scc1 .Lhs_skip
	v_readlane_b32 s14, v254, 46
	v_readlane_b32 s4, v254, 24
	s_add_i32 s2, s76, s14
	v_bfe_u32 v57, v76, 3, 1
	v_readlane_b32 s5, v254, 25
	v_and_b32_e32 v2, 0x1c0, v84
	s_nop 0
	v_mov_b64_e32 v[46:47], s[4:5]
	s_movk_i32 s10, 0x1e00
	v_lshlrev_b32_e32 v48, 1, v2
	v_mov_b32_e32 v49, v4
	v_lshrrev_b32_e32 v119, 5, v5
	v_and_b32_e32 v74, 48, v5
	v_mov_b32_e32 v75, v4
	s_mov_b64 s[12:13], 0x1900
	s_or_b32 s3, s2, 2
	s_movk_i32 s11, 0x1000
	s_or_b32 s3, s2, 4
	s_or_b32 s3, s2, 6
	s_or_b32 s3, s2, 8
	s_or_b32 s3, s2, 10
	s_or_b32 s3, s2, 12
	v_or_b32_e32 v54, s3, v57
	v_mad_u64_u32 v[54:55], s[4:5], v54, s10, v[46:47]
	v_lshl_add_u64 v[54:55], v[54:55], 0, v[48:49]
	v_lshl_add_u64 v[54:55], v[54:55], 0, v[74:75]
	v_add_co_u32_e32 v56, vcc, s11, v54
	s_mov_b64 s[6:7], vcc
	s_or_b32 s4, s2, 14
	v_and_b32_e32 v77, 15, v76
	v_readlane_b32 s2, v254, 47
	s_nop 1
	v_or_b32_e32 v66, s2, v77
	v_mov_b32_e32 v67, v4
	v_readlane_b32 s2, v254, 26
	v_lshlrev_b64 v[66:67], 7, v[66:67]
	v_readlane_b32 s3, v254, 27
	s_nop 1
	v_lshl_add_u64 v[66:67], s[2:3], 0, v[66:67]
	v_lshl_add_u64 v[70:71], v[66:67], 0, v[74:75]
	v_cmp_lt_i32_e32 vcc, v227, v226
	global_load_dwordx4 v[66:69], v[70:71], off offset:64
	global_load_dwordx4 v[70:73], v[70:71], off
	v_readlane_b32 s98, v254, 24
	v_readlane_b32 s99, v254, 25
	v_readlane_b32 s100, v254, 46
	v_bfe_u32 v86, v252, 3, 1
	v_lshrrev_b32_e32 v87, 5, v5
	v_and_b32_e32 v88, 7, v5
	s_add_i32 s100, s100, s76
	s_add_i32 s100, s100, s85
	v_and_b32_e32 v89, 48, v5
	v_lshl_or_b32 v88, v88, 7, v89
	v_or_b32_e32 v86, s100, v86
	v_or_b32_e32 v87, s100, v87
	s_movk_i32 s101, 0x1900
	s_movk_i32 s100, 0x1d90
	v_mul_u32_u24_e32 v86, 0x1e00, v86
	v_mul_u32_u24_e32 v87, 0x1e00, v87
	v_lshrrev_b32_e32 v89, 1, v5
	v_and_b32_e32 v89, 8, v89
	v_add3_u32 v86, v86, v88, s101
	v_add3_u32 v87, v87, v89, s100
	global_load_dwordx4 v[90:93], v86, s[98:99] nt
	global_load_dwordx4 v[94:97], v86, s[98:99] offset:64 nt
	global_load_dwordx2 v[98:99], v87, s[98:99]
	s_lshl_b32 s100, s85, 10
	s_lshl_b32 s101, s85, 8
	v_lshl_add_u32 v88, v5, 4, s100
	v_lshl_add_u32 v89, v5, 3, s101
	s_waitcnt vmcnt(0)
	ds_write_b128 v88, v[90:93]
	ds_write_b128 v88, v[94:97] offset:1024
	ds_write_b64 v89, v[98:99] offset:16384
	s_waitcnt lgkmcnt(0)
	s_barrier
	v_lshlrev_b32_e32 v88, 4, v5
	v_lshlrev_b32_e32 v89, 3, v5
	ds_read_b128 v[0:3], v88 offset:0
	ds_read_b128 v[6:9], v88 offset:1024
	ds_read_b128 v[14:17], v88 offset:2048
	ds_read_b128 v[10:13], v88 offset:3072
	ds_read_b128 v[18:21], v88 offset:4096
	ds_read_b128 v[22:25], v88 offset:5120
	ds_read_b128 v[30:33], v88 offset:6144
	ds_read_b128 v[26:29], v88 offset:7168
	ds_read_b128 v[34:37], v88 offset:8192
	ds_read_b128 v[38:41], v88 offset:9216
	ds_read_b128 v[42:45], v88 offset:10240
	ds_read_b128 v[50:53], v88 offset:11264
	ds_read_b128 v[54:57], v88 offset:12288
	ds_read_b128 v[58:61], v88 offset:13312
	ds_read_b128 v[46:49], v88 offset:14336
	ds_read_b128 v[62:65], v88 offset:15360
	ds_read_b64 v[78:79], v89 offset:16384
	ds_read_b64 v[80:81], v89 offset:16896
	ds_read_b64 v[82:83], v89 offset:17408
	ds_read_b64 v[100:101], v89 offset:17920
	ds_read_b64 v[104:105], v89 offset:18432
	ds_read_b64 v[108:109], v89 offset:18944
	ds_read_b64 v[112:113], v89 offset:19456
	ds_read_b64 v[116:117], v89 offset:19968
	s_waitcnt lgkmcnt(0)
	s_barrier
	s_waitcnt vmcnt(0)
	v_lshlrev_b32_e32 v93, 16, v82
	v_and_b32_e32 v94, 0xffff0000, v82
	v_lshlrev_b32_e32 v95, 16, v83
	v_and_b32_e32 v96, 0xffff0000, v83
	v_lshl_add_u64 v[82:83], s[2:3], 0, v[74:75]
	v_cndmask_b32_e32 v74, v253, v227, vcc
	v_lshlrev_b32_e32 v118, 2, v74
	v_and_b32_e32 v74, 16, v76
	v_cmp_eq_u32_e64 s[6:7], 0, v74
	v_lshlrev_b32_e32 v74, 2, v77
	v_lshl_or_b32 v74, v119, 13, v74
	v_readlane_b32 s2, v254, 36
	v_lshlrev_b32_e32 v85, 16, v78
	v_and_b32_e32 v86, 0xffff0000, v78
	v_lshlrev_b32_e32 v87, 16, v79
	v_and_b32_e32 v88, 0xffff0000, v79
	v_lshlrev_b32_e32 v89, 16, v80
	v_and_b32_e32 v90, 0xffff0000, v80
	v_lshlrev_b32_e32 v91, 16, v81
	v_and_b32_e32 v92, 0xffff0000, v81
	v_lshlrev_b32_e32 v97, 16, v100
	v_and_b32_e32 v98, 0xffff0000, v100
	v_lshlrev_b32_e32 v99, 16, v101
	v_and_b32_e32 v100, 0xffff0000, v101
	v_lshlrev_b32_e32 v101, 16, v104
	v_and_b32_e32 v102, 0xffff0000, v104
	v_lshlrev_b32_e32 v103, 16, v105
	v_and_b32_e32 v104, 0xffff0000, v105
	v_lshlrev_b32_e32 v105, 16, v108
	v_and_b32_e32 v106, 0xffff0000, v108
	v_lshlrev_b32_e32 v107, 16, v109
	v_and_b32_e32 v108, 0xffff0000, v109
	v_add_u32_e32 v119, s2, v74
	v_readlane_b32 s10, v254, 4
	v_lshlrev_b32_e32 v109, 16, v112
	v_and_b32_e32 v110, 0xffff0000, v112
	v_lshlrev_b32_e32 v111, 16, v113
	v_and_b32_e32 v112, 0xffff0000, v113
	v_lshlrev_b32_e32 v113, 16, v116
	v_and_b32_e32 v114, 0xffff0000, v116
	v_lshlrev_b32_e32 v115, 16, v117
	v_and_b32_e32 v116, 0xffff0000, v117
	v_or_b32_e32 v117, s14, v77
	s_branch .LBB0_1085
	.p2alignl 6, 3212836864

; __device__ __forceinline__ void indexer_unit(const Args& a, LAS unsigned char* lds, LAS unsigned long long* maskl, int b, int qblk, int wave, int lane) {
;     ...
;             unsigned T = 0u; bool exact = false; const int ng = (nr + 3) >> 2;
; #pragma unroll 1
.Ltk_ld_done:
	s_mov_b32 s10, 0
	s_mov_b32 s11, 31
	.p2alignl 6, 3212836864

; #define DSA_GLOAD(kt, RK, RV) do { const GAS char* kb_ = ckb + (size_t)(kt) * (64 * 256); const GAS char* vb_ = cvb + (size_t)(kt) * 128; \
;         RK[0] = *(const GAS u32x4*)(kb_ + (size_t)vok0); RK[1] = *(const GAS u32x4*)(kb_ + (size_t)vok1); \
;         RV[0] = *(const GAS u32x4*)(vb_ + (size_t)vov0); RV[1] = *(const GAS u32x4*)(vb_ + (size_t)vov1); } while (0)
; __device__ __forceinline__ void dsa_unit32(const Args& a, LAS unsigned char* lds, const LAS unsigned long long* maskl, int b, int qb, int tid, int wave, int lane) {
;     ...
; #pragma unroll 1
;     for (int kt = 0; kt < nkt; kt += 2) {
;         if (kt + 2 < nkt) DSA_GLOAD(kt + 2, rk0, rv0);
;         compute(0, kt);
;         if (kt + 1 < nkt) DSA_LSTORE(1, rk1, rv1);
;         __syncthreads();
;         if (kt + 1 >= nkt) break;
;         if (kt + 3 < nkt) DSA_GLOAD(kt + 3, rk1, rv1);
;         compute(1, kt + 1);
;         if (kt + 2 < nkt) DSA_LSTORE(0, rk0, rv0);
;         __syncthreads();
;     }
.LBB0_1301:
	s_mov_b64 s[0:1], 0x100
	s_add_i32 s5, s5, 2
	v_lshl_add_u64 v[186:187], v[186:187], 0, s[0:1]
	v_lshl_add_u64 v[188:189], v[188:189], 0, s[0:1]
	s_mov_b64 s[0:1], 0x8000
	s_cmp_ge_u32 s6, s4
	v_lshl_add_u64 v[190:191], v[190:191], 0, s[0:1]
	v_lshl_add_u64 v[192:193], v[192:193], 0, s[0:1]
	v_add_u32_e32 v206, 16, v206
	s_cselect_b64 s[2:3], -1, 0
	s_waitcnt lgkmcnt(0)
	s_barrier
	s_and_b64 vcc, exec, s[2:3]
	s_cbranch_vccnz .LBB0_1073
	.p2alignl 6, 3212836864
